# phase 4: dynamic per-XCD tile claiming so copier blocks take GEMM tiles after the copy queue empties; copier stop threshold 781
# baseline (speedup 1.0000x reference)
.Lcp1_entry:
	v_readfirstlane_b32 s0, v192
	v_lshlrev_b32_e32 v16, 4, v192
	s_add_u32 s4, s38, 0xc7b7100
	s_addc_u32 s5, s39, 0
	s_add_u32 s6, s38, 0xc7b7200
	s_addc_u32 s7, s39, 0
	s_lshr_b32 s0, s0, 6
	s_mov_b32 s1, 0
	s_mov_b32 s30, 2
	v_mov_b32_e32 v93, 0
	v_mov_b32_e32 v94, 1
	v_mov_b32_e32 v95, 16
	v_mov_b32_e32 v96, 20
	v_add_u32_e32 v17, 0x2000, v16
	v_add_u32_e32 v18, 0x4000, v16
	v_add_u32_e32 v19, 0x6000, v16
	v_add_u32_e32 v20, 0x8000, v16
	v_add_u32_e32 v21, 0xa000, v16
	v_add_u32_e32 v22, 0xc000, v16
	v_add_u32_e32 v23, 0xe000, v16
	v_add_u32_e32 v104, 0x10000, v16
	v_add_u32_e32 v105, 0x12000, v16
	v_add_u32_e32 v106, 0x14000, v16
	v_add_u32_e32 v107, 0x16000, v16
	v_add_u32_e32 v108, 0x18000, v16
	v_add_u32_e32 v109, 0x1a000, v16
	v_add_u32_e32 v110, 0x1c000, v16
	v_add_u32_e32 v111, 0x1e000, v16
	s_barrier
	s_cmp_lg_u32 s0, 0
	s_cbranch_scc1 .Lcp1_p0
	s_mov_b64 s[22:23], exec
	s_mov_b64 exec, 1
	global_load_dword v118, v93, s[6:7] sc1
	v_mov_b32_e32 v117, 0xa80
	s_waitcnt vmcnt(0)
	v_readfirstlane_b32 s25, v118
	s_cmpk_gt_u32 s25, 0x30c
	s_cbranch_scc1 .Lcp1_pnone
	v_mov_b32_e32 v117, 2
	global_atomic_add v117, v93, v117, s[4:5] sc0
	s_waitcnt vmcnt(0)

.Lcp1_ac_A_j:
	s_lshl_b32 s18, s18, 17
	v_add_u32_e32 v92, s24, v16
	s_add_u32 s14, s36, s19
	s_addc_u32 s15, s37, 0
	s_add_u32 s14, s14, s18
	s_addc_u32 s15, s15, 0
	s_add_u32 s12, s12, s18
	s_addc_u32 s13, s13, 0
	s_add_u32 s12, s12, 0x2000
	s_addc_u32 s13, s13, 0
	global_load_dwordx4 v[180:183], v16, s[12:13] nt
	global_load_dwordx4 v[184:187], v17, s[12:13] nt
	global_load_dwordx4 v[188:191], v18, s[12:13] nt
	global_load_dwordx4 v[196:199], v19, s[12:13] nt
	global_load_dwordx4 v[200:203], v20, s[12:13] nt
	global_load_dwordx4 v[204:207], v21, s[12:13] nt
	global_load_dwordx4 v[208:211], v22, s[12:13] nt
	global_load_dwordx4 v[212:215], v23, s[12:13] nt
	global_load_dwordx4 v[216:219], v104, s[12:13] nt
	global_load_dwordx4 v[220:223], v105, s[12:13] nt
	global_load_dwordx4 v[224:227], v106, s[12:13] nt
	global_load_dwordx4 v[228:231], v107, s[12:13] nt
	global_load_dwordx4 v[244:247], v108, s[12:13] nt
	global_load_dwordx4 v[248:251], v109, s[12:13] nt
	global_load_dwordx4 v[4:7], v110, s[12:13] nt
	global_load_dwordx4 v[8:11], v92, s[12:13] nt
	s_waitcnt vmcnt(31)
	global_store_dwordx4 v16, v[30:33], s[10:11] nt
	s_waitcnt vmcnt(31)
	global_store_dwordx4 v17, v[34:37], s[10:11] nt
	s_waitcnt vmcnt(31)
	global_store_dwordx4 v18, v[38:41], s[10:11] nt
	s_waitcnt vmcnt(31)
	global_store_dwordx4 v19, v[42:45], s[10:11] nt
	s_waitcnt vmcnt(31)
	global_store_dwordx4 v20, v[46:49], s[10:11] nt
	s_waitcnt vmcnt(31)
	global_store_dwordx4 v21, v[50:53], s[10:11] nt
	s_waitcnt vmcnt(31)
	global_store_dwordx4 v22, v[54:57], s[10:11] nt
	s_waitcnt vmcnt(31)
	global_store_dwordx4 v23, v[58:61], s[10:11] nt
	s_waitcnt vmcnt(31)
	global_store_dwordx4 v104, v[62:65], s[10:11] nt
	s_waitcnt vmcnt(31)
	global_store_dwordx4 v105, v[66:69], s[10:11] nt
	s_waitcnt vmcnt(31)
	global_store_dwordx4 v106, v[70:73], s[10:11] nt
	s_waitcnt vmcnt(31)
	global_store_dwordx4 v107, v[74:77], s[10:11] nt
	s_waitcnt vmcnt(31)
	global_store_dwordx4 v108, v[164:167], s[10:11] nt
	s_waitcnt vmcnt(31)
	global_store_dwordx4 v109, v[168:171], s[10:11] nt
	s_waitcnt vmcnt(31)
	global_store_dwordx4 v110, v[172:175], s[10:11] nt
	s_waitcnt vmcnt(31)
	global_store_dwordx4 v91, v[176:179], s[10:11] nt
	s_cmp_lg_u32 s0, 0
	s_cbranch_scc1 .Lcp1_A_s4
	s_mov_b64 s[22:23], exec
	s_mov_b64 exec, 1
	s_cmp_lg_u32 s1, 0
	s_cbranch_scc1 .Lcp1_A_s4stop
	s_waitcnt vmcnt(32)
	v_readfirstlane_b32 s25, v118
	s_cmpk_gt_u32 s25, 0x30c
	s_cselect_b32 s1, 1, 0
	v_readfirstlane_b32 s26, v117
	s_cmpk_ge_u32 s26, 0xa80
	s_cselect_b32 s27, 1, 0
	s_or_b32 s1, s1, s27
	s_branch .Lcp1_A_s4pub

.Lcp1_ac_B_j:
	s_lshl_b32 s18, s18, 17
	v_add_u32_e32 v91, s24, v16
	s_add_u32 s10, s36, s19
	s_addc_u32 s11, s37, 0
	s_add_u32 s10, s10, s18
	s_addc_u32 s11, s11, 0
	s_add_u32 s8, s8, s18
	s_addc_u32 s9, s9, 0
	s_add_u32 s8, s8, 0x2000
	s_addc_u32 s9, s9, 0
	global_load_dwordx4 v[30:33], v16, s[8:9] nt
	global_load_dwordx4 v[34:37], v17, s[8:9] nt
	global_load_dwordx4 v[38:41], v18, s[8:9] nt
	global_load_dwordx4 v[42:45], v19, s[8:9] nt
	global_load_dwordx4 v[46:49], v20, s[8:9] nt
	global_load_dwordx4 v[50:53], v21, s[8:9] nt
	global_load_dwordx4 v[54:57], v22, s[8:9] nt
	global_load_dwordx4 v[58:61], v23, s[8:9] nt
	global_load_dwordx4 v[62:65], v104, s[8:9] nt
	global_load_dwordx4 v[66:69], v105, s[8:9] nt
	global_load_dwordx4 v[70:73], v106, s[8:9] nt
	global_load_dwordx4 v[74:77], v107, s[8:9] nt
	global_load_dwordx4 v[164:167], v108, s[8:9] nt
	global_load_dwordx4 v[168:171], v109, s[8:9] nt
	global_load_dwordx4 v[172:175], v110, s[8:9] nt
	global_load_dwordx4 v[176:179], v91, s[8:9] nt
	s_waitcnt vmcnt(31)
	global_store_dwordx4 v16, v[180:183], s[14:15] nt
	s_waitcnt vmcnt(31)
	global_store_dwordx4 v17, v[184:187], s[14:15] nt
	s_waitcnt vmcnt(31)
	global_store_dwordx4 v18, v[188:191], s[14:15] nt
	s_waitcnt vmcnt(31)
	global_store_dwordx4 v19, v[196:199], s[14:15] nt
	s_waitcnt vmcnt(31)
	global_store_dwordx4 v20, v[200:203], s[14:15] nt
	s_waitcnt vmcnt(31)
	global_store_dwordx4 v21, v[204:207], s[14:15] nt
	s_waitcnt vmcnt(31)
	global_store_dwordx4 v22, v[208:211], s[14:15] nt
	s_waitcnt vmcnt(31)
	global_store_dwordx4 v23, v[212:215], s[14:15] nt
	s_waitcnt vmcnt(31)
	global_store_dwordx4 v104, v[216:219], s[14:15] nt
	s_waitcnt vmcnt(31)
	global_store_dwordx4 v105, v[220:223], s[14:15] nt
	s_waitcnt vmcnt(31)
	global_store_dwordx4 v106, v[224:227], s[14:15] nt
	s_waitcnt vmcnt(31)
	global_store_dwordx4 v107, v[228:231], s[14:15] nt
	s_waitcnt vmcnt(31)
	global_store_dwordx4 v108, v[244:247], s[14:15] nt
	s_waitcnt vmcnt(31)
	global_store_dwordx4 v109, v[248:251], s[14:15] nt
	s_waitcnt vmcnt(31)
	global_store_dwordx4 v110, v[4:7], s[14:15] nt
	s_waitcnt vmcnt(31)
	global_store_dwordx4 v92, v[8:11], s[14:15] nt
	s_cmp_lg_u32 s0, 0
	s_cbranch_scc1 .Lcp1_B_s4
	s_mov_b64 s[22:23], exec
	s_mov_b64 exec, 1
	s_cmp_lg_u32 s1, 0
	s_cbranch_scc1 .Lcp1_B_s4stop
	s_waitcnt vmcnt(32)
	v_readfirstlane_b32 s25, v118
	s_cmpk_gt_u32 s25, 0x30c
	s_cselect_b32 s1, 1, 0
	v_readfirstlane_b32 s26, v117
	s_cmpk_ge_u32 s26, 0xa80
	s_cselect_b32 s27, 1, 0
	s_or_b32 s1, s1, s27
	s_branch .Lcp1_B_s4pub
